# ph0 adaLN GEMV: all 16 weight-row loads of an item issued up front (k loop unrolled) instead of 4 per iteration
# speedup vs baseline: 1.0063x; 1.0063x over previous
.LBB0_1105:
	v_add_u32_e32 v27, 0, v47
	v_mad_i64_i32 v[28:29], s[34:35], v27, s25, v[20:21]
	global_load_dwordx4 v[92:95], v[28:29], off nt
	v_add_u32_e32 v27, 8, v47
	v_mad_i64_i32 v[28:29], s[34:35], v27, s25, v[20:21]
	global_load_dwordx4 v[96:99], v[28:29], off nt
	v_add_u32_e32 v27, 16, v47
	v_mad_i64_i32 v[28:29], s[34:35], v27, s25, v[20:21]
	global_load_dwordx4 v[100:103], v[28:29], off nt
	v_add_u32_e32 v27, 24, v47
	v_mad_i64_i32 v[28:29], s[34:35], v27, s25, v[20:21]
	global_load_dwordx4 v[104:107], v[28:29], off nt
	v_add_u32_e32 v27, 32, v47
	v_mad_i64_i32 v[28:29], s[34:35], v27, s25, v[20:21]
	global_load_dwordx4 v[108:111], v[28:29], off nt
	v_add_u32_e32 v27, 40, v47
	v_mad_i64_i32 v[28:29], s[34:35], v27, s25, v[20:21]
	global_load_dwordx4 v[112:115], v[28:29], off nt
	v_add_u32_e32 v27, 48, v47
	v_mad_i64_i32 v[28:29], s[34:35], v27, s25, v[20:21]
	global_load_dwordx4 v[116:119], v[28:29], off nt
	v_add_u32_e32 v27, 56, v47
	v_mad_i64_i32 v[28:29], s[34:35], v27, s25, v[20:21]
	global_load_dwordx4 v[120:123], v[28:29], off nt
	v_add_u32_e32 v27, 64, v47
	v_mad_i64_i32 v[28:29], s[34:35], v27, s25, v[20:21]
	global_load_dwordx4 v[124:127], v[28:29], off nt
	v_add_u32_e32 v27, 72, v47
	v_mad_i64_i32 v[28:29], s[34:35], v27, s25, v[20:21]
	global_load_dwordx4 v[128:131], v[28:29], off nt
	v_add_u32_e32 v27, 80, v47
	v_mad_i64_i32 v[28:29], s[34:35], v27, s25, v[20:21]
	global_load_dwordx4 v[132:135], v[28:29], off nt
	v_add_u32_e32 v27, 88, v47
	v_mad_i64_i32 v[28:29], s[34:35], v27, s25, v[20:21]
	global_load_dwordx4 v[136:139], v[28:29], off nt
	v_add_u32_e32 v27, 96, v47
	v_mad_i64_i32 v[28:29], s[34:35], v27, s25, v[20:21]
	global_load_dwordx4 v[140:143], v[28:29], off nt
	v_add_u32_e32 v27, 104, v47
	v_mad_i64_i32 v[28:29], s[34:35], v27, s25, v[20:21]
	global_load_dwordx4 v[144:147], v[28:29], off nt
	v_add_u32_e32 v27, 112, v47
	v_mad_i64_i32 v[28:29], s[34:35], v27, s25, v[20:21]
	global_load_dwordx4 v[148:151], v[28:29], off nt
	v_add_u32_e32 v27, 120, v47
	v_mad_i64_i32 v[28:29], s[34:35], v27, s25, v[20:21]
	global_load_dwordx4 v[152:155], v[28:29], off nt
	ds_read2_b32 v[52:53], v26 offset1:8
	v_add_u32_e32 v27, 0x1000, v26
	v_add_u32_e32 v68, 0x3000, v26
	v_add_u32_e32 v70, 0x4000, v26
	v_add_u32_e32 v51, 0x2000, v26
	ds_read2_b32 v[54:55], v26 offset0:16 offset1:24
	ds_read2_b32 v[56:57], v27 offset1:8
	ds_read2_b32 v[58:59], v51 offset1:8
	ds_read2_b32 v[60:61], v68 offset1:8
	ds_read2_b32 v[62:63], v70 offset1:8
	ds_read2_b32 v[64:65], v27 offset0:16 offset1:24
	ds_read2_b32 v[66:67], v51 offset0:16 offset1:24
	ds_read2_b32 v[68:69], v68 offset0:16 offset1:24
	ds_read2_b32 v[70:71], v70 offset0:16 offset1:24
	s_waitcnt lgkmcnt(9)
	v_mov_b32_e32 v72, v53
	s_waitcnt lgkmcnt(7)
	v_mov_b32_e32 v76, v57
	s_waitcnt lgkmcnt(6)
	v_mov_b32_e32 v78, v59
	s_waitcnt lgkmcnt(5)
	v_mov_b32_e32 v80, v61
	s_waitcnt lgkmcnt(4)
	v_mov_b32_e32 v82, v63
	v_mov_b32_e32 v74, v55
	s_waitcnt lgkmcnt(3)
	v_mov_b32_e32 v84, v65
	s_waitcnt lgkmcnt(2)
	v_mov_b32_e32 v86, v67
	s_waitcnt lgkmcnt(1)
	v_mov_b32_e32 v88, v69
	s_waitcnt lgkmcnt(0)
	v_mov_b32_e32 v90, v71
	v_add_u32_e32 v26, 0x80, v26
	s_waitcnt vmcnt(15)
	v_pk_fma_f32 v[24:25], v[92:93], v[52:53], v[24:25] op_sel_hi:[1,0,1]
	v_pk_fma_f32 v[22:23], v[94:95], v[52:53], v[22:23] op_sel_hi:[1,0,1]
	v_pk_fma_f32 v[18:19], v[92:93], v[56:57], v[18:19] op_sel_hi:[1,0,1]
	v_pk_fma_f32 v[16:17], v[94:95], v[56:57], v[16:17] op_sel_hi:[1,0,1]
	v_pk_fma_f32 v[14:15], v[92:93], v[58:59], v[14:15] op_sel_hi:[1,0,1]
	v_pk_fma_f32 v[12:13], v[94:95], v[58:59], v[12:13] op_sel_hi:[1,0,1]
	v_pk_fma_f32 v[10:11], v[92:93], v[60:61], v[10:11] op_sel_hi:[1,0,1]
	v_pk_fma_f32 v[8:9], v[94:95], v[60:61], v[8:9] op_sel_hi:[1,0,1]
	v_pk_fma_f32 v[6:7], v[92:93], v[62:63], v[6:7] op_sel_hi:[1,0,1]
	v_pk_fma_f32 v[4:5], v[94:95], v[62:63], v[4:5] op_sel_hi:[1,0,1]
	s_waitcnt vmcnt(14)
	v_pk_fma_f32 v[22:23], v[98:99], v[72:73], v[22:23] op_sel_hi:[1,0,1]
	v_pk_fma_f32 v[24:25], v[96:97], v[72:73], v[24:25] op_sel_hi:[1,0,1]
	v_pk_fma_f32 v[16:17], v[98:99], v[76:77], v[16:17] op_sel_hi:[1,0,1]
	v_pk_fma_f32 v[18:19], v[96:97], v[76:77], v[18:19] op_sel_hi:[1,0,1]
	v_pk_fma_f32 v[12:13], v[98:99], v[78:79], v[12:13] op_sel_hi:[1,0,1]
	v_pk_fma_f32 v[14:15], v[96:97], v[78:79], v[14:15] op_sel_hi:[1,0,1]
	v_pk_fma_f32 v[8:9], v[98:99], v[80:81], v[8:9] op_sel_hi:[1,0,1]
	v_pk_fma_f32 v[10:11], v[96:97], v[80:81], v[10:11] op_sel_hi:[1,0,1]
	v_pk_fma_f32 v[4:5], v[98:99], v[82:83], v[4:5] op_sel_hi:[1,0,1]
	v_pk_fma_f32 v[6:7], v[96:97], v[82:83], v[6:7] op_sel_hi:[1,0,1]
	s_waitcnt vmcnt(13)
	v_pk_fma_f32 v[24:25], v[100:101], v[54:55], v[24:25] op_sel_hi:[1,0,1]
	v_pk_fma_f32 v[22:23], v[102:103], v[54:55], v[22:23] op_sel_hi:[1,0,1]
	v_pk_fma_f32 v[18:19], v[100:101], v[64:65], v[18:19] op_sel_hi:[1,0,1]
	v_pk_fma_f32 v[16:17], v[102:103], v[64:65], v[16:17] op_sel_hi:[1,0,1]
	v_pk_fma_f32 v[14:15], v[100:101], v[66:67], v[14:15] op_sel_hi:[1,0,1]
	v_pk_fma_f32 v[12:13], v[102:103], v[66:67], v[12:13] op_sel_hi:[1,0,1]
	v_pk_fma_f32 v[10:11], v[100:101], v[68:69], v[10:11] op_sel_hi:[1,0,1]
	v_pk_fma_f32 v[8:9], v[102:103], v[68:69], v[8:9] op_sel_hi:[1,0,1]
	v_pk_fma_f32 v[6:7], v[100:101], v[70:71], v[6:7] op_sel_hi:[1,0,1]
	v_pk_fma_f32 v[4:5], v[102:103], v[70:71], v[4:5] op_sel_hi:[1,0,1]
	s_waitcnt vmcnt(12)
	v_pk_fma_f32 v[22:23], v[106:107], v[74:75], v[22:23] op_sel_hi:[1,0,1]
	v_pk_fma_f32 v[24:25], v[104:105], v[74:75], v[24:25] op_sel_hi:[1,0,1]
	v_pk_fma_f32 v[16:17], v[106:107], v[84:85], v[16:17] op_sel_hi:[1,0,1]
	v_pk_fma_f32 v[18:19], v[104:105], v[84:85], v[18:19] op_sel_hi:[1,0,1]
	v_pk_fma_f32 v[12:13], v[106:107], v[86:87], v[12:13] op_sel_hi:[1,0,1]
	v_pk_fma_f32 v[14:15], v[104:105], v[86:87], v[14:15] op_sel_hi:[1,0,1]
	v_pk_fma_f32 v[8:9], v[106:107], v[88:89], v[8:9] op_sel_hi:[1,0,1]
	v_pk_fma_f32 v[10:11], v[104:105], v[88:89], v[10:11] op_sel_hi:[1,0,1]
	v_pk_fma_f32 v[4:5], v[106:107], v[90:91], v[4:5] op_sel_hi:[1,0,1]
	v_pk_fma_f32 v[6:7], v[104:105], v[90:91], v[6:7] op_sel_hi:[1,0,1]
	ds_read2_b32 v[52:53], v26 offset1:8
	v_add_u32_e32 v27, 0x1000, v26
	v_add_u32_e32 v68, 0x3000, v26
	v_add_u32_e32 v70, 0x4000, v26
	v_add_u32_e32 v51, 0x2000, v26
	ds_read2_b32 v[54:55], v26 offset0:16 offset1:24
	ds_read2_b32 v[56:57], v27 offset1:8
	ds_read2_b32 v[58:59], v51 offset1:8
	ds_read2_b32 v[60:61], v68 offset1:8
	ds_read2_b32 v[62:63], v70 offset1:8
	ds_read2_b32 v[64:65], v27 offset0:16 offset1:24
	ds_read2_b32 v[66:67], v51 offset0:16 offset1:24
	ds_read2_b32 v[68:69], v68 offset0:16 offset1:24
	ds_read2_b32 v[70:71], v70 offset0:16 offset1:24
	s_waitcnt lgkmcnt(9)
	v_mov_b32_e32 v72, v53
	s_waitcnt lgkmcnt(7)
	v_mov_b32_e32 v76, v57
	s_waitcnt lgkmcnt(6)
	v_mov_b32_e32 v78, v59
	s_waitcnt lgkmcnt(5)
	v_mov_b32_e32 v80, v61
	s_waitcnt lgkmcnt(4)
	v_mov_b32_e32 v82, v63
	v_mov_b32_e32 v74, v55
	s_waitcnt lgkmcnt(3)
	v_mov_b32_e32 v84, v65
	s_waitcnt lgkmcnt(2)
	v_mov_b32_e32 v86, v67
	s_waitcnt lgkmcnt(1)
	v_mov_b32_e32 v88, v69
	s_waitcnt lgkmcnt(0)
	v_mov_b32_e32 v90, v71
	v_add_u32_e32 v26, 0x80, v26
	s_waitcnt vmcnt(11)
	v_pk_fma_f32 v[24:25], v[108:109], v[52:53], v[24:25] op_sel_hi:[1,0,1]
	v_pk_fma_f32 v[22:23], v[110:111], v[52:53], v[22:23] op_sel_hi:[1,0,1]
	v_pk_fma_f32 v[18:19], v[108:109], v[56:57], v[18:19] op_sel_hi:[1,0,1]
	v_pk_fma_f32 v[16:17], v[110:111], v[56:57], v[16:17] op_sel_hi:[1,0,1]
	v_pk_fma_f32 v[14:15], v[108:109], v[58:59], v[14:15] op_sel_hi:[1,0,1]
	v_pk_fma_f32 v[12:13], v[110:111], v[58:59], v[12:13] op_sel_hi:[1,0,1]
	v_pk_fma_f32 v[10:11], v[108:109], v[60:61], v[10:11] op_sel_hi:[1,0,1]
	v_pk_fma_f32 v[8:9], v[110:111], v[60:61], v[8:9] op_sel_hi:[1,0,1]
	v_pk_fma_f32 v[6:7], v[108:109], v[62:63], v[6:7] op_sel_hi:[1,0,1]
	v_pk_fma_f32 v[4:5], v[110:111], v[62:63], v[4:5] op_sel_hi:[1,0,1]
	s_waitcnt vmcnt(10)
	v_pk_fma_f32 v[22:23], v[114:115], v[72:73], v[22:23] op_sel_hi:[1,0,1]
	v_pk_fma_f32 v[24:25], v[112:113], v[72:73], v[24:25] op_sel_hi:[1,0,1]
	v_pk_fma_f32 v[16:17], v[114:115], v[76:77], v[16:17] op_sel_hi:[1,0,1]
	v_pk_fma_f32 v[18:19], v[112:113], v[76:77], v[18:19] op_sel_hi:[1,0,1]
	v_pk_fma_f32 v[12:13], v[114:115], v[78:79], v[12:13] op_sel_hi:[1,0,1]
	v_pk_fma_f32 v[14:15], v[112:113], v[78:79], v[14:15] op_sel_hi:[1,0,1]
	v_pk_fma_f32 v[8:9], v[114:115], v[80:81], v[8:9] op_sel_hi:[1,0,1]
	v_pk_fma_f32 v[10:11], v[112:113], v[80:81], v[10:11] op_sel_hi:[1,0,1]
	v_pk_fma_f32 v[4:5], v[114:115], v[82:83], v[4:5] op_sel_hi:[1,0,1]
	v_pk_fma_f32 v[6:7], v[112:113], v[82:83], v[6:7] op_sel_hi:[1,0,1]
	s_waitcnt vmcnt(9)
	v_pk_fma_f32 v[24:25], v[116:117], v[54:55], v[24:25] op_sel_hi:[1,0,1]
	v_pk_fma_f32 v[22:23], v[118:119], v[54:55], v[22:23] op_sel_hi:[1,0,1]
	v_pk_fma_f32 v[18:19], v[116:117], v[64:65], v[18:19] op_sel_hi:[1,0,1]
	v_pk_fma_f32 v[16:17], v[118:119], v[64:65], v[16:17] op_sel_hi:[1,0,1]
	v_pk_fma_f32 v[14:15], v[116:117], v[66:67], v[14:15] op_sel_hi:[1,0,1]
	v_pk_fma_f32 v[12:13], v[118:119], v[66:67], v[12:13] op_sel_hi:[1,0,1]
	v_pk_fma_f32 v[10:11], v[116:117], v[68:69], v[10:11] op_sel_hi:[1,0,1]
	v_pk_fma_f32 v[8:9], v[118:119], v[68:69], v[8:9] op_sel_hi:[1,0,1]
	v_pk_fma_f32 v[6:7], v[116:117], v[70:71], v[6:7] op_sel_hi:[1,0,1]
	v_pk_fma_f32 v[4:5], v[118:119], v[70:71], v[4:5] op_sel_hi:[1,0,1]
	s_waitcnt vmcnt(8)
	v_pk_fma_f32 v[22:23], v[122:123], v[74:75], v[22:23] op_sel_hi:[1,0,1]
	v_pk_fma_f32 v[24:25], v[120:121], v[74:75], v[24:25] op_sel_hi:[1,0,1]
	v_pk_fma_f32 v[16:17], v[122:123], v[84:85], v[16:17] op_sel_hi:[1,0,1]
	v_pk_fma_f32 v[18:19], v[120:121], v[84:85], v[18:19] op_sel_hi:[1,0,1]
	v_pk_fma_f32 v[12:13], v[122:123], v[86:87], v[12:13] op_sel_hi:[1,0,1]
	v_pk_fma_f32 v[14:15], v[120:121], v[86:87], v[14:15] op_sel_hi:[1,0,1]
	v_pk_fma_f32 v[8:9], v[122:123], v[88:89], v[8:9] op_sel_hi:[1,0,1]
	v_pk_fma_f32 v[10:11], v[120:121], v[88:89], v[10:11] op_sel_hi:[1,0,1]
	v_pk_fma_f32 v[4:5], v[122:123], v[90:91], v[4:5] op_sel_hi:[1,0,1]
	v_pk_fma_f32 v[6:7], v[120:121], v[90:91], v[6:7] op_sel_hi:[1,0,1]
	ds_read2_b32 v[52:53], v26 offset1:8
	v_add_u32_e32 v27, 0x1000, v26
	v_add_u32_e32 v68, 0x3000, v26
	v_add_u32_e32 v70, 0x4000, v26
	v_add_u32_e32 v51, 0x2000, v26
	ds_read2_b32 v[54:55], v26 offset0:16 offset1:24
	ds_read2_b32 v[56:57], v27 offset1:8
	ds_read2_b32 v[58:59], v51 offset1:8
	ds_read2_b32 v[60:61], v68 offset1:8
	ds_read2_b32 v[62:63], v70 offset1:8
	ds_read2_b32 v[64:65], v27 offset0:16 offset1:24
	ds_read2_b32 v[66:67], v51 offset0:16 offset1:24
	ds_read2_b32 v[68:69], v68 offset0:16 offset1:24
	ds_read2_b32 v[70:71], v70 offset0:16 offset1:24
	s_waitcnt lgkmcnt(9)
	v_mov_b32_e32 v72, v53
	s_waitcnt lgkmcnt(7)
	v_mov_b32_e32 v76, v57
	s_waitcnt lgkmcnt(6)
	v_mov_b32_e32 v78, v59
	s_waitcnt lgkmcnt(5)
	v_mov_b32_e32 v80, v61
	s_waitcnt lgkmcnt(4)
	v_mov_b32_e32 v82, v63
	v_mov_b32_e32 v74, v55
	s_waitcnt lgkmcnt(3)
	v_mov_b32_e32 v84, v65
	s_waitcnt lgkmcnt(2)
	v_mov_b32_e32 v86, v67
	s_waitcnt lgkmcnt(1)
	v_mov_b32_e32 v88, v69
	s_waitcnt lgkmcnt(0)
	v_mov_b32_e32 v90, v71
	v_add_u32_e32 v26, 0x80, v26
	s_waitcnt vmcnt(7)
	v_pk_fma_f32 v[24:25], v[124:125], v[52:53], v[24:25] op_sel_hi:[1,0,1]
	v_pk_fma_f32 v[22:23], v[126:127], v[52:53], v[22:23] op_sel_hi:[1,0,1]
	v_pk_fma_f32 v[18:19], v[124:125], v[56:57], v[18:19] op_sel_hi:[1,0,1]
	v_pk_fma_f32 v[16:17], v[126:127], v[56:57], v[16:17] op_sel_hi:[1,0,1]
	v_pk_fma_f32 v[14:15], v[124:125], v[58:59], v[14:15] op_sel_hi:[1,0,1]
	v_pk_fma_f32 v[12:13], v[126:127], v[58:59], v[12:13] op_sel_hi:[1,0,1]
	v_pk_fma_f32 v[10:11], v[124:125], v[60:61], v[10:11] op_sel_hi:[1,0,1]
	v_pk_fma_f32 v[8:9], v[126:127], v[60:61], v[8:9] op_sel_hi:[1,0,1]
	v_pk_fma_f32 v[6:7], v[124:125], v[62:63], v[6:7] op_sel_hi:[1,0,1]
	v_pk_fma_f32 v[4:5], v[126:127], v[62:63], v[4:5] op_sel_hi:[1,0,1]
	s_waitcnt vmcnt(6)
	v_pk_fma_f32 v[22:23], v[130:131], v[72:73], v[22:23] op_sel_hi:[1,0,1]
	v_pk_fma_f32 v[24:25], v[128:129], v[72:73], v[24:25] op_sel_hi:[1,0,1]
	v_pk_fma_f32 v[16:17], v[130:131], v[76:77], v[16:17] op_sel_hi:[1,0,1]
	v_pk_fma_f32 v[18:19], v[128:129], v[76:77], v[18:19] op_sel_hi:[1,0,1]
	v_pk_fma_f32 v[12:13], v[130:131], v[78:79], v[12:13] op_sel_hi:[1,0,1]
	v_pk_fma_f32 v[14:15], v[128:129], v[78:79], v[14:15] op_sel_hi:[1,0,1]
	v_pk_fma_f32 v[8:9], v[130:131], v[80:81], v[8:9] op_sel_hi:[1,0,1]
	v_pk_fma_f32 v[10:11], v[128:129], v[80:81], v[10:11] op_sel_hi:[1,0,1]
	v_pk_fma_f32 v[4:5], v[130:131], v[82:83], v[4:5] op_sel_hi:[1,0,1]
	v_pk_fma_f32 v[6:7], v[128:129], v[82:83], v[6:7] op_sel_hi:[1,0,1]
	s_waitcnt vmcnt(5)
	v_pk_fma_f32 v[24:25], v[132:133], v[54:55], v[24:25] op_sel_hi:[1,0,1]
	v_pk_fma_f32 v[22:23], v[134:135], v[54:55], v[22:23] op_sel_hi:[1,0,1]
	v_pk_fma_f32 v[18:19], v[132:133], v[64:65], v[18:19] op_sel_hi:[1,0,1]
	v_pk_fma_f32 v[16:17], v[134:135], v[64:65], v[16:17] op_sel_hi:[1,0,1]
	v_pk_fma_f32 v[14:15], v[132:133], v[66:67], v[14:15] op_sel_hi:[1,0,1]
	v_pk_fma_f32 v[12:13], v[134:135], v[66:67], v[12:13] op_sel_hi:[1,0,1]
	v_pk_fma_f32 v[10:11], v[132:133], v[68:69], v[10:11] op_sel_hi:[1,0,1]
	v_pk_fma_f32 v[8:9], v[134:135], v[68:69], v[8:9] op_sel_hi:[1,0,1]
	v_pk_fma_f32 v[6:7], v[132:133], v[70:71], v[6:7] op_sel_hi:[1,0,1]
	v_pk_fma_f32 v[4:5], v[134:135], v[70:71], v[4:5] op_sel_hi:[1,0,1]
	s_waitcnt vmcnt(4)
	v_pk_fma_f32 v[22:23], v[138:139], v[74:75], v[22:23] op_sel_hi:[1,0,1]
	v_pk_fma_f32 v[24:25], v[136:137], v[74:75], v[24:25] op_sel_hi:[1,0,1]
	v_pk_fma_f32 v[16:17], v[138:139], v[84:85], v[16:17] op_sel_hi:[1,0,1]
	v_pk_fma_f32 v[18:19], v[136:137], v[84:85], v[18:19] op_sel_hi:[1,0,1]
	v_pk_fma_f32 v[12:13], v[138:139], v[86:87], v[12:13] op_sel_hi:[1,0,1]
	v_pk_fma_f32 v[14:15], v[136:137], v[86:87], v[14:15] op_sel_hi:[1,0,1]
	v_pk_fma_f32 v[8:9], v[138:139], v[88:89], v[8:9] op_sel_hi:[1,0,1]
	v_pk_fma_f32 v[10:11], v[136:137], v[88:89], v[10:11] op_sel_hi:[1,0,1]
	v_pk_fma_f32 v[4:5], v[138:139], v[90:91], v[4:5] op_sel_hi:[1,0,1]
	v_pk_fma_f32 v[6:7], v[136:137], v[90:91], v[6:7] op_sel_hi:[1,0,1]
	ds_read2_b32 v[52:53], v26 offset1:8
	v_add_u32_e32 v27, 0x1000, v26
	v_add_u32_e32 v68, 0x3000, v26
	v_add_u32_e32 v70, 0x4000, v26
	v_add_u32_e32 v51, 0x2000, v26
	ds_read2_b32 v[54:55], v26 offset0:16 offset1:24
	ds_read2_b32 v[56:57], v27 offset1:8
	ds_read2_b32 v[58:59], v51 offset1:8
	ds_read2_b32 v[60:61], v68 offset1:8
	ds_read2_b32 v[62:63], v70 offset1:8
	ds_read2_b32 v[64:65], v27 offset0:16 offset1:24
	ds_read2_b32 v[66:67], v51 offset0:16 offset1:24
	ds_read2_b32 v[68:69], v68 offset0:16 offset1:24
	ds_read2_b32 v[70:71], v70 offset0:16 offset1:24
	s_waitcnt lgkmcnt(9)
	v_mov_b32_e32 v72, v53
	s_waitcnt lgkmcnt(7)
	v_mov_b32_e32 v76, v57
	s_waitcnt lgkmcnt(6)
	v_mov_b32_e32 v78, v59
	s_waitcnt lgkmcnt(5)
	v_mov_b32_e32 v80, v61
	s_waitcnt lgkmcnt(4)
	v_mov_b32_e32 v82, v63
	v_mov_b32_e32 v74, v55
	s_waitcnt lgkmcnt(3)
	v_mov_b32_e32 v84, v65
	s_waitcnt lgkmcnt(2)
	v_mov_b32_e32 v86, v67
	s_waitcnt lgkmcnt(1)
	v_mov_b32_e32 v88, v69
	s_waitcnt lgkmcnt(0)
	v_mov_b32_e32 v90, v71
	v_add_u32_e32 v26, 0x80, v26
	s_waitcnt vmcnt(3)
	v_pk_fma_f32 v[24:25], v[140:141], v[52:53], v[24:25] op_sel_hi:[1,0,1]
	v_pk_fma_f32 v[22:23], v[142:143], v[52:53], v[22:23] op_sel_hi:[1,0,1]
	v_pk_fma_f32 v[18:19], v[140:141], v[56:57], v[18:19] op_sel_hi:[1,0,1]
	v_pk_fma_f32 v[16:17], v[142:143], v[56:57], v[16:17] op_sel_hi:[1,0,1]
	v_pk_fma_f32 v[14:15], v[140:141], v[58:59], v[14:15] op_sel_hi:[1,0,1]
	v_pk_fma_f32 v[12:13], v[142:143], v[58:59], v[12:13] op_sel_hi:[1,0,1]
	v_pk_fma_f32 v[10:11], v[140:141], v[60:61], v[10:11] op_sel_hi:[1,0,1]
	v_pk_fma_f32 v[8:9], v[142:143], v[60:61], v[8:9] op_sel_hi:[1,0,1]
	v_pk_fma_f32 v[6:7], v[140:141], v[62:63], v[6:7] op_sel_hi:[1,0,1]
	v_pk_fma_f32 v[4:5], v[142:143], v[62:63], v[4:5] op_sel_hi:[1,0,1]
	s_waitcnt vmcnt(2)
	v_pk_fma_f32 v[22:23], v[146:147], v[72:73], v[22:23] op_sel_hi:[1,0,1]
	v_pk_fma_f32 v[24:25], v[144:145], v[72:73], v[24:25] op_sel_hi:[1,0,1]
	v_pk_fma_f32 v[16:17], v[146:147], v[76:77], v[16:17] op_sel_hi:[1,0,1]
	v_pk_fma_f32 v[18:19], v[144:145], v[76:77], v[18:19] op_sel_hi:[1,0,1]
	v_pk_fma_f32 v[12:13], v[146:147], v[78:79], v[12:13] op_sel_hi:[1,0,1]
	v_pk_fma_f32 v[14:15], v[144:145], v[78:79], v[14:15] op_sel_hi:[1,0,1]
	v_pk_fma_f32 v[8:9], v[146:147], v[80:81], v[8:9] op_sel_hi:[1,0,1]
	v_pk_fma_f32 v[10:11], v[144:145], v[80:81], v[10:11] op_sel_hi:[1,0,1]
	v_pk_fma_f32 v[4:5], v[146:147], v[82:83], v[4:5] op_sel_hi:[1,0,1]
	v_pk_fma_f32 v[6:7], v[144:145], v[82:83], v[6:7] op_sel_hi:[1,0,1]
	s_waitcnt vmcnt(1)
	v_pk_fma_f32 v[24:25], v[148:149], v[54:55], v[24:25] op_sel_hi:[1,0,1]
	v_pk_fma_f32 v[22:23], v[150:151], v[54:55], v[22:23] op_sel_hi:[1,0,1]
	v_pk_fma_f32 v[18:19], v[148:149], v[64:65], v[18:19] op_sel_hi:[1,0,1]
	v_pk_fma_f32 v[16:17], v[150:151], v[64:65], v[16:17] op_sel_hi:[1,0,1]
	v_pk_fma_f32 v[14:15], v[148:149], v[66:67], v[14:15] op_sel_hi:[1,0,1]
	v_pk_fma_f32 v[12:13], v[150:151], v[66:67], v[12:13] op_sel_hi:[1,0,1]
	v_pk_fma_f32 v[10:11], v[148:149], v[68:69], v[10:11] op_sel_hi:[1,0,1]
	v_pk_fma_f32 v[8:9], v[150:151], v[68:69], v[8:9] op_sel_hi:[1,0,1]
	v_pk_fma_f32 v[6:7], v[148:149], v[70:71], v[6:7] op_sel_hi:[1,0,1]
	v_pk_fma_f32 v[4:5], v[150:151], v[70:71], v[4:5] op_sel_hi:[1,0,1]
	s_waitcnt vmcnt(0)
	v_pk_fma_f32 v[22:23], v[154:155], v[74:75], v[22:23] op_sel_hi:[1,0,1]
	v_pk_fma_f32 v[24:25], v[152:153], v[74:75], v[24:25] op_sel_hi:[1,0,1]
	v_pk_fma_f32 v[16:17], v[154:155], v[84:85], v[16:17] op_sel_hi:[1,0,1]
	v_pk_fma_f32 v[18:19], v[152:153], v[84:85], v[18:19] op_sel_hi:[1,0,1]
	v_pk_fma_f32 v[12:13], v[154:155], v[86:87], v[12:13] op_sel_hi:[1,0,1]
	v_pk_fma_f32 v[14:15], v[152:153], v[86:87], v[14:15] op_sel_hi:[1,0,1]
	v_pk_fma_f32 v[8:9], v[154:155], v[88:89], v[8:9] op_sel_hi:[1,0,1]
	v_pk_fma_f32 v[10:11], v[152:153], v[88:89], v[10:11] op_sel_hi:[1,0,1]
	v_pk_fma_f32 v[4:5], v[154:155], v[90:91], v[4:5] op_sel_hi:[1,0,1]
	v_pk_fma_f32 v[6:7], v[152:153], v[90:91], v[6:7] op_sel_hi:[1,0,1]
	ds_bpermute_b32 v20, v3, v24
	ds_bpermute_b32 v21, v3, v25
	ds_bpermute_b32 v26, v3, v22
	ds_bpermute_b32 v27, v3, v23
	ds_bpermute_b32 v36, v3, v10
	ds_bpermute_b32 v37, v3, v11
	s_waitcnt lgkmcnt(4)
	v_pk_add_f32 v[20:21], v[24:25], v[20:21]
	ds_bpermute_b32 v24, v45, v20
	s_waitcnt lgkmcnt(3)
	v_pk_add_f32 v[26:27], v[22:23], v[26:27]
	ds_bpermute_b32 v25, v45, v21
	ds_bpermute_b32 v28, v45, v26
	ds_bpermute_b32 v29, v45, v27
	ds_bpermute_b32 v30, v3, v18
	ds_bpermute_b32 v31, v3, v19
	s_waitcnt lgkmcnt(6)
	v_pk_add_f32 v[10:11], v[10:11], v[36:37]
	s_waitcnt lgkmcnt(4)
	v_pk_add_f32 v[20:21], v[20:21], v[24:25]
	s_waitcnt lgkmcnt(2)
	v_pk_add_f32 v[24:25], v[26:27], v[28:29]
	ds_bpermute_b32 v32, v3, v14
	s_waitcnt lgkmcnt(1)
	v_pk_add_f32 v[26:27], v[18:19], v[30:31]
	ds_bpermute_b32 v30, v3, v16
	ds_bpermute_b32 v31, v3, v17
	ds_bpermute_b32 v33, v3, v15
	ds_bpermute_b32 v34, v3, v12
	ds_bpermute_b32 v35, v3, v13
	ds_bpermute_b32 v36, v45, v10
	ds_bpermute_b32 v37, v45, v11
	ds_bpermute_b32 v38, v3, v8
	ds_bpermute_b32 v39, v3, v9
	ds_bpermute_b32 v40, v3, v6
	ds_bpermute_b32 v41, v3, v7
	ds_bpermute_b32 v42, v3, v4
	ds_bpermute_b32 v43, v3, v5
	s_waitcnt lgkmcnt(11)
	v_pk_add_f32 v[16:17], v[16:17], v[30:31]
	s_waitcnt lgkmcnt(10)
	v_pk_add_f32 v[14:15], v[14:15], v[32:33]
	s_waitcnt lgkmcnt(8)
	v_pk_add_f32 v[12:13], v[12:13], v[34:35]
	s_waitcnt lgkmcnt(6)
	v_pk_add_f32 v[10:11], v[10:11], v[36:37]
	s_waitcnt lgkmcnt(4)
	v_pk_add_f32 v[36:37], v[8:9], v[38:39]
	s_waitcnt lgkmcnt(2)
	v_pk_add_f32 v[6:7], v[6:7], v[40:41]
	s_waitcnt lgkmcnt(0)
	v_pk_add_f32 v[42:43], v[4:5], v[42:43]
	ds_bpermute_b32 v28, v45, v26
	ds_bpermute_b32 v29, v45, v27
	ds_bpermute_b32 v30, v45, v16
	ds_bpermute_b32 v31, v45, v17
	ds_bpermute_b32 v32, v45, v14
	ds_bpermute_b32 v33, v45, v15
	ds_bpermute_b32 v34, v45, v12
	ds_bpermute_b32 v35, v45, v13
	ds_bpermute_b32 v38, v45, v36
	ds_bpermute_b32 v39, v45, v37
	ds_bpermute_b32 v40, v45, v6
	ds_bpermute_b32 v41, v45, v7
	ds_bpermute_b32 v52, v45, v42
	ds_bpermute_b32 v53, v45, v43
	s_waitcnt lgkmcnt(12)
	v_pk_add_f32 v[26:27], v[26:27], v[28:29]
	s_waitcnt lgkmcnt(10)
	v_pk_add_f32 v[16:17], v[16:17], v[30:31]
	s_waitcnt lgkmcnt(8)
	v_pk_add_f32 v[14:15], v[14:15], v[32:33]
	s_waitcnt lgkmcnt(6)
	v_pk_add_f32 v[12:13], v[12:13], v[34:35]
	s_waitcnt lgkmcnt(4)
	v_pk_add_f32 v[36:37], v[36:37], v[38:39]
	s_waitcnt lgkmcnt(2)
	v_pk_add_f32 v[4:5], v[6:7], v[40:41]
	s_waitcnt lgkmcnt(0)
	v_pk_add_f32 v[40:41], v[42:43], v[52:53]
	ds_bpermute_b32 v22, v46, v20
	ds_bpermute_b32 v23, v46, v21
	ds_bpermute_b32 v18, v46, v24
	ds_bpermute_b32 v19, v46, v25
	ds_bpermute_b32 v28, v46, v26
	ds_bpermute_b32 v29, v46, v27
	ds_bpermute_b32 v30, v46, v16
	ds_bpermute_b32 v31, v46, v17
	ds_bpermute_b32 v32, v46, v14
	ds_bpermute_b32 v33, v46, v15
	ds_bpermute_b32 v34, v46, v12
	ds_bpermute_b32 v35, v46, v13
	ds_bpermute_b32 v8, v46, v10
	ds_bpermute_b32 v9, v46, v11
	ds_bpermute_b32 v38, v46, v36
	ds_bpermute_b32 v39, v46, v37
	ds_bpermute_b32 v6, v46, v4
	ds_bpermute_b32 v7, v46, v5
	ds_bpermute_b32 v42, v46, v40
	ds_bpermute_b32 v43, v46, v41
	s_and_saveexec_b64 s[2:3], s[38:39]
	s_cbranch_execz .LBB0_1108
	s_waitcnt lgkmcnt(14)
	v_pk_add_f32 v[20:21], v[20:21], v[22:23]
	v_pk_add_f32 v[22:23], v[24:25], v[18:19]
	ds_write_b128 v49, v[20:23] offset:20480
	v_pk_add_f32 v[18:19], v[26:27], v[28:29]
	s_waitcnt lgkmcnt(13)
	v_pk_add_f32 v[20:21], v[16:17], v[30:31]
	s_waitcnt lgkmcnt(11)
	v_pk_add_f32 v[14:15], v[14:15], v[32:33]
	s_waitcnt lgkmcnt(9)
	v_pk_add_f32 v[16:17], v[12:13], v[34:35]
	s_waitcnt lgkmcnt(7)
	v_pk_add_f32 v[8:9], v[10:11], v[8:9]
	s_waitcnt lgkmcnt(5)
	v_pk_add_f32 v[10:11], v[36:37], v[38:39]
	s_waitcnt lgkmcnt(3)
	v_pk_add_f32 v[4:5], v[4:5], v[6:7]
	s_waitcnt lgkmcnt(1)
	v_pk_add_f32 v[6:7], v[40:41], v[42:43]
	ds_write_b128 v49, v[18:21] offset:20608
	ds_write_b128 v49, v[14:17] offset:20736
	ds_write_b128 v49, v[8:11] offset:20864
	ds_write_b128 v49, v[4:7] offset:20992
